# v26 + diff-attention loop uses 4 LDS K/V buffer sets (base toggled by v_xor 64KB) so the 2 write-after-read barriers per 2 tiles are removed
# speedup vs baseline: 1.0040x; 1.0040x over previous
; #define SBAR() __builtin_amdgcn_sched_barrier(0)
; #define SLOAD(k0) do { vs0 = *(const bf16x8*)(vp0 + (long)(k0) * ldv); vs1 = *(const bf16x8*)(vp0 + (long)((k0) + 32) * ldv); \
;     ksg[0] = *(const bf16x8*)(kp0 + (long)(k0) * ldk0); \
;     if constexpr (DQK == 192) { ksg[1] = *(const bf16x8*)(kp0 + (long)((k0) + 32) * ldk0); ksg[2] = *(const bf16x8*)(kp2 + (long)(k0) * ldk1); } } while (0)
; #define SWRITE(b) do { *(bf16x8*)(V_lds + (b) * SHM_V + vst0) = vs0; *(bf16x8*)(V_lds + (b) * SHM_V + vst1) = vs1; \
;     *(bf16x8*)(K_lds + (b) * SHM_K + koff0) = ksg[0]; \
;     if constexpr (DQK == 192) { *(bf16x8*)(K_lds + (b) * SHM_K + koff1) = ksg[1]; *(bf16x8*)(K_lds + (b) * SHM_K + koff2) = ksg[2]; } } while (0)
; #define SWAIT() asm volatile("s_waitcnt vmcnt(0)" ::: "memory")
; DEVI void finishSM(f32x16& p0, f32x16& p1, float alpha, float& l_reg, bf16x8& pa0, bf16x8& pa1, bf16x8& pa2, bf16x8& pa3) {
; #pragma unroll
;   for (int r = 0; r < 16; ++r) p1[r] = __builtin_amdgcn_exp2f(p1[r]);
;   float ps = 0;
; #pragma unroll
;   for (int r = 0; r < 16; ++r) ps += p0[r];
; #pragma unroll
;   for (int r = 0; r < 16; ++r) ps += p1[r];
;   { auto rr = __builtin_amdgcn_permlane32_swap(__float_as_uint(ps), __float_as_uint(ps), false, false);
;     ps = __uint_as_float(rr[0]) + __uint_as_float(rr[1]); }
;   l_reg = l_reg * alpha + ps;
;   PK4(p0, 0, pa0); PK4(p0, 8, pa1); PK4(p1, 0, pa2); PK4(p1, 8, pa3);
; template <int DQK, bool PIPE>
; DEVI void attn_body(const u16* __restrict__ Qb, int ldq, const u16* __restrict__ K0, int ldk0, const u16* __restrict__ K1, int ldk1,
;                     const u16* __restrict__ Vh, int ldv, u16* __restrict__ Ob, int ldo, int seq, float scale, char* lds) {
;     ...
;   bf16x8 pa0, pa1, pa2, pa3; const int NT = seq / 64;
;   if constexpr (PIPE) {
;     f32x16 pA0, pA1, pB0, pB1; float mnA, mnB, alA, alB;
;     SLOAD(0); SWAIT(); SWRITE(0); __syncthreads();
;     QKT(pA0, pA1, K_lds); partialSM(pA0, pA1, m_reg, mnA, alA, scale);
;     SLOAD(64);
;     SWAIT(); SWRITE(1); __syncthreads();
;     for (int j = 1; j + 1 < NT; j += 2) {
;       SBAR(); QKT(pB0, pB1, K_lds + SHM_K);
;       finishSM(pA0, pA1, alA, l_reg, pa0, pa1, pa2, pa3); SBAR();
;       SLOAD((j + 1) * 64); SBAR();
;       pv_d0(o, vb0, pa0, pa1, pa2, pa3); partialSM(pB0, pB1, m_reg, mnB, alB, scale);
.Ldiff_prio_skip:
	v_xor_b32_e32 v140, 0x10000, v140
	v_xor_b32_e32 v141, 0x10000, v141
	v_xor_b32_e32 v142, 0x10000, v142
.LBB0_469:
	ds_read_b128 v[64:67], v143 offset:40960
	ds_read_b128 v[68:71], v143 offset:45056
	v_add_f32_e32 v149, 0, v157
	v_add_f32_e32 v149, v159, v149
	v_add_f32_e32 v149, v161, v149
	s_waitcnt lgkmcnt(1)
	v_mfma_f32_32x32x16_bf16 v[80:95], v[64:67], v[100:103], 0
	v_add_f32_e32 v149, v163, v149
	v_add_f32_e32 v149, v165, v149
	ds_read_b128 v[150:153], v144 offset:40960
	ds_read_b128 v[172:175], v144 offset:45056
	v_add_f32_e32 v149, v167, v149
	v_add_f32_e32 v149, v168, v149
	v_add_f32_e32 v149, v170, v149
	v_add_f32_e32 v149, v155, v149
	s_waitcnt lgkmcnt(2)
	v_mfma_f32_32x32x16_bf16 v[64:79], v[68:71], v[100:103], 0
	v_add_f32_e32 v149, v156, v149
	v_add_f32_e32 v149, v158, v149
	v_add_f32_e32 v149, v160, v149
	v_exp_f32_e32 v132, v132
	v_add_f32_e32 v149, v162, v149
	v_exp_f32_e32 v133, v133
	v_add_f32_e32 v149, v164, v149
	s_waitcnt lgkmcnt(1)
	v_mfma_f32_32x32x16_bf16 v[80:95], v[150:153], v[96:99], v[80:95]
	v_exp_f32_e32 v130, v130
	v_add_f32_e32 v149, v166, v149
	v_exp_f32_e32 v131, v131
	v_add_f32_e32 v149, v169, v149
	v_exp_f32_e32 v120, v120
	v_add_f32_e32 v149, v132, v149
	v_exp_f32_e32 v121, v121
	s_waitcnt lgkmcnt(0)
	v_mfma_f32_32x32x16_bf16 v[64:79], v[172:175], v[96:99], v[64:79]
	ds_read_b128 v[150:153], v146 offset:40960
	ds_read_b128 v[172:175], v146 offset:45056
	v_add_f32_e32 v149, v133, v149
	v_exp_f32_e32 v116, v116
	v_add_f32_e32 v149, v130, v149
	v_exp_f32_e32 v117, v117
	v_add_f32_e32 v149, v131, v149
	v_exp_f32_e32 v114, v114
	s_waitcnt lgkmcnt(1)
	v_mfma_f32_32x32x16_bf16 v[80:95], v[150:153], v[108:111], v[80:95]
	v_add_f32_e32 v149, v120, v149
	v_exp_f32_e32 v115, v115
	v_add_f32_e32 v149, v121, v149
	v_exp_f32_e32 v122, v122
	v_add_f32_e32 v149, v116, v149
	v_exp_f32_e32 v123, v123
	v_add_f32_e32 v149, v117, v149
	s_waitcnt lgkmcnt(0)
	v_mfma_f32_32x32x16_bf16 v[64:79], v[172:175], v[108:111], v[64:79]
	ds_read_b128 v[150:153], v145 offset:40960
	ds_read_b128 v[172:175], v145 offset:45056
	v_xor_b32_e32 v143, 0x10000, v143
	v_xor_b32_e32 v144, 0x10000, v144
	v_xor_b32_e32 v145, 0x10000, v145
	v_xor_b32_e32 v146, 0x10000, v146
	v_exp_f32_e32 v118, v118
	v_add_f32_e32 v149, v114, v149
	v_exp_f32_e32 v119, v119
	v_add_f32_e32 v149, v115, v149
	v_exp_f32_e32 v112, v112
	v_add_f32_e32 v149, v122, v149
	s_waitcnt lgkmcnt(1)
	v_mfma_f32_32x32x16_bf16 v[80:95], v[150:153], v[104:107], v[80:95]
	v_exp_f32_e32 v113, v113
	v_add_f32_e32 v149, v123, v149
	v_add_f32_e32 v149, v118, v149
	v_add_f32_e32 v149, v119, v149
	v_add_f32_e32 v149, v112, v149
	v_add_f32_e32 v149, v113, v149
	v_mov_b32_e32 v150, v149
	s_waitcnt lgkmcnt(0)
	v_mfma_f32_32x32x16_bf16 v[64:79], v[172:175], v[104:107], v[64:79]
	v_cvt_pk_bf16_f32 v152, v155, v156
	v_cvt_pk_bf16_f32 v154, v162, v164
	v_permlane32_swap_b32_e32 v149, v150
	v_cvt_pk_bf16_f32 v172, v157, v159
	v_cvt_pk_bf16_f32 v173, v161, v163
	v_cvt_pk_bf16_f32 v174, v165, v167
	v_cvt_pk_bf16_f32 v175, v168, v170
	v_cvt_pk_bf16_f32 v153, v158, v160
	v_cvt_pk_bf16_f32 v155, v166, v169
	v_permlane32_swap_b32_e32 v152, v154
	v_cvt_pk_bf16_f32 v156, v132, v133
	v_cvt_pk_bf16_f32 v157, v130, v131
	v_cvt_pk_bf16_f32 v158, v120, v121
	v_cvt_pk_bf16_f32 v159, v116, v117
	v_cvt_pk_bf16_f32 v160, v114, v115
	v_cvt_pk_bf16_f32 v161, v122, v123
	v_cvt_pk_bf16_f32 v162, v118, v119
	v_cvt_pk_bf16_f32 v163, v112, v113
	v_permlane32_swap_b32_e32 v172, v174
	v_permlane32_swap_b32_e32 v173, v175
	v_permlane32_swap_b32_e32 v153, v155
	v_permlane32_swap_b32_e32 v156, v158
	v_permlane32_swap_b32_e32 v157, v159
	v_permlane32_swap_b32_e32 v160, v162
	v_permlane32_swap_b32_e32 v161, v163
	v_lshl_add_u64 v[130:131], v[126:127], 0, s[36:37]
	s_mov_b32 s8, 0x814f000
	v_add_co_u32_e32 v112, vcc, s8, v130
	s_mov_b32 s8, 0x81e7000
	s_nop 0
	v_addc_co_u32_e32 v113, vcc, 0, v131, vcc
	v_add_co_u32_e32 v116, vcc, s8, v130
	v_lshl_add_u64 v[132:133], v[128:129], 0, s[36:37]
	s_nop 0
	v_addc_co_u32_e32 v117, vcc, 0, v131, vcc
	s_mov_b32 s8, 0x814e000
	v_add_co_u32_e32 v120, vcc, s8, v132
	global_load_dwordx4 v[112:115], v[112:113], off
	s_nop 0
	global_load_dwordx4 v[116:119], v[116:117], off
	v_addc_co_u32_e32 v121, vcc, 0, v133, vcc
	global_load_dwordx4 v[120:123], v[120:121], off offset:2048
	ds_read_b64_tr_b16 v[164:165], v139 offset:0
	ds_read_b64_tr_b16 v[166:167], v139 offset:0x800
	ds_read_b64_tr_b16 v[168:169], v139 offset:0x1000
	ds_read_b64_tr_b16 v[170:171], v139 offset:0x1800
	ds_read_b64_tr_b16 v[176:177], v139 offset:0x2000
	ds_read_b64_tr_b16 v[178:179], v139 offset:0x2800
	ds_read_b64_tr_b16 v[180:181], v139 offset:0x3000
	ds_read_b64_tr_b16 v[182:183], v139 offset:0x3800
	s_waitcnt lgkmcnt(0)
	s_nop 0
	v_mfma_f32_32x32x16_bf16 v[0:15], v[172:175], v[164:167], v[0:15]
	ds_read_b64_tr_b16 v[164:165], v139 offset:0x200
	ds_read_b64_tr_b16 v[166:167], v139 offset:0xa00
	v_mfma_f32_32x32x16_bf16 v[0:15], v[152:155], v[168:171], v[0:15]
	ds_read_b64_tr_b16 v[168:169], v139 offset:0x1200
	ds_read_b64_tr_b16 v[170:171], v139 offset:0x1a00
	v_mfma_f32_32x32x16_bf16 v[0:15], v[156:159], v[176:179], v[0:15]
	ds_read_b64_tr_b16 v[176:177], v139 offset:0x2200
	ds_read_b64_tr_b16 v[178:179], v139 offset:0x2a00
	v_mfma_f32_32x32x16_bf16 v[0:15], v[160:163], v[180:183], v[0:15]
	ds_read_b64_tr_b16 v[180:181], v139 offset:0x3200
	ds_read_b64_tr_b16 v[182:183], v139 offset:0x3a00
	s_waitcnt lgkmcnt(0)
; template <int D0> DEVI void pv_one(f32x16& od, int vb, bf16x8 pa0, bf16x8 pa1, bf16x8 pa2, bf16x8 pa3) {
;     ...
;   od = __builtin_amdgcn_mfma_f32_32x32x16_bf16(pa0, PK(l0, h0), od, 0, 0, 0);
;   od = __builtin_amdgcn_mfma_f32_32x32x16_bf16(pa1, PK(l1, h1), od, 0, 0, 0);
;   od = __builtin_amdgcn_mfma_f32_32x32x16_bf16(pa2, PK(l2, h2), od, 0, 0, 0);
;   od = __builtin_amdgcn_mfma_f32_32x32x16_bf16(pa3, PK(l3, h3), od, 0, 0, 0);
;     ...
; }
; DEVI void pv_d0(f32x16* o, int vb, bf16x8 pa0, bf16x8 pa1, bf16x8 pa2, bf16x8 pa3) {
;   pv_one<0>(o[0], vb, pa0, pa1, pa2, pa3); pv_one<1>(o[1], vb, pa0, pa1, pa2, pa3); pv_one<2>(o[2], vb, pa0, pa1, pa2, pa3); pv_one<3>(o[3], vb, pa0, pa1, pa2, pa3);
; }
; DEVI void partialSM(f32x16& p0, f32x16& p1, float& m_reg, float& mn, float& alpha, float scale) {
;   const float C = scale * 1.4426950408889634f;
;   float pmax = p0[0];
; #pragma unroll
;   for (int r = 1; r < 16; ++r) pmax = fmaxf(pmax, p0[r]);
; #pragma unroll
;   for (int r = 0; r < 16; ++r) pmax = fmaxf(pmax, p1[r]);
;   { auto rr = __builtin_amdgcn_permlane32_swap(__float_as_uint(pmax), __float_as_uint(pmax), false, false);
;     pmax = fmaxf(__uint_as_float(rr[0]), __uint_as_float(rr[1])); }
;   if (__builtin_expect(__all(pmax - m_reg <= ATT_THR / scale), 1)) { mn = m_reg; alpha = 1.f; }
;   else { mn = fmaxf(m_reg, pmax); alpha = __builtin_amdgcn_exp2f((m_reg - mn) * C); m_reg = mn; }
; template <int DQK, bool PIPE>
; DEVI void attn_body(const u16* __restrict__ Qb, int ldq, const u16* __restrict__ K0, int ldk0, const u16* __restrict__ K1, int ldk1,
;                     const u16* __restrict__ Vh, int ldv, u16* __restrict__ Ob, int ldo, int seq, float scale, char* lds) {
;     ...
;   bf16x8 pa0, pa1, pa2, pa3; const int NT = seq / 64;
;   if constexpr (PIPE) {
;     f32x16 pA0, pA1, pB0, pB1; float mnA, mnB, alA, alB;
;     SLOAD(0); SWAIT(); SWRITE(0); __syncthreads();
;     QKT(pA0, pA1, K_lds); partialSM(pA0, pA1, m_reg, mnA, alA, scale);
;     SLOAD(64);
;     SWAIT(); SWRITE(1); __syncthreads();
;     for (int j = 1; j + 1 < NT; j += 2) {
;       SBAR(); QKT(pB0, pB1, K_lds + SHM_K);
;       finishSM(pA0, pA1, alA, l_reg, pa0, pa1, pa2, pa3); SBAR();
;       SLOAD((j + 1) * 64); SBAR();
;       pv_d0(o, vb0, pa0, pa1, pa2, pa3); partialSM(pB0, pB1, m_reg, mnB, alB, scale);
;       __syncthreads(); SWAIT(); SWRITE(0);
;       RESC(alB); __syncthreads();
	v_mfma_f32_32x32x16_bf16 v[48:63], v[172:175], v[164:167], v[48:63]
	ds_read_b64_tr_b16 v[164:165], v139 offset:0x400
	ds_read_b64_tr_b16 v[166:167], v139 offset:0xc00
	v_mfma_f32_32x32x16_bf16 v[48:63], v[152:155], v[168:171], v[48:63]
	ds_read_b64_tr_b16 v[168:169], v139 offset:0x1400
	ds_read_b64_tr_b16 v[170:171], v139 offset:0x1c00
	v_mfma_f32_32x32x16_bf16 v[48:63], v[156:159], v[176:179], v[48:63]
	ds_read_b64_tr_b16 v[176:177], v139 offset:0x2400
	ds_read_b64_tr_b16 v[178:179], v139 offset:0x2c00
	v_mfma_f32_32x32x16_bf16 v[48:63], v[160:163], v[180:183], v[48:63]
	ds_read_b64_tr_b16 v[180:181], v139 offset:0x3400
	ds_read_b64_tr_b16 v[182:183], v139 offset:0x3c00
	s_waitcnt lgkmcnt(0)
	v_mfma_f32_32x32x16_bf16 v[32:47], v[172:175], v[164:167], v[32:47]
	ds_read_b64_tr_b16 v[164:165], v139 offset:0x600
	ds_read_b64_tr_b16 v[166:167], v139 offset:0xe00
	v_mfma_f32_32x32x16_bf16 v[32:47], v[152:155], v[168:171], v[32:47]
	ds_read_b64_tr_b16 v[168:169], v139 offset:0x1600
	ds_read_b64_tr_b16 v[170:171], v139 offset:0x1e00
	v_mfma_f32_32x32x16_bf16 v[32:47], v[156:159], v[176:179], v[32:47]
	ds_read_b64_tr_b16 v[176:177], v139 offset:0x2600
	ds_read_b64_tr_b16 v[178:179], v139 offset:0x2e00
	v_mfma_f32_32x32x16_bf16 v[32:47], v[160:163], v[180:183], v[32:47]
	ds_read_b64_tr_b16 v[180:181], v139 offset:0x3600
	ds_read_b64_tr_b16 v[182:183], v139 offset:0x3e00
	s_waitcnt lgkmcnt(0)
	v_mfma_f32_32x32x16_bf16 v[16:31], v[172:175], v[164:167], v[16:31]
	v_max_f32_e32 v151, v81, v81
	s_waitcnt vmcnt(0)
	s_waitcnt vmcnt(2)
	ds_write_b128 v141, v[112:115]
	s_waitcnt vmcnt(1)
	ds_write_b128 v142, v[116:119]
	s_waitcnt vmcnt(0)
	ds_write_b128 v140, v[120:123] offset:32768
	v_mfma_f32_32x32x16_bf16 v[16:31], v[152:155], v[168:171], v[16:31]
	v_max_f32_e32 v152, v80, v80
	v_max_f32_e32 v151, v152, v151
	v_max3_f32 v151, v151, v82, v83
	v_max3_f32 v151, v151, v84, v85
	v_max3_f32 v151, v151, v86, v87
	v_max3_f32 v151, v151, v88, v89
	v_max3_f32 v151, v151, v90, v91
	v_max3_f32 v151, v151, v92, v93
	v_max3_f32 v151, v151, v94, v95
	v_max3_f32 v151, v151, v64, v65
	v_max3_f32 v151, v151, v66, v67
	v_max3_f32 v151, v151, v68, v69
	v_max3_f32 v151, v151, v70, v71
	v_max3_f32 v151, v151, v72, v73
	v_max3_f32 v151, v151, v74, v75
	v_max3_f32 v151, v151, v76, v77
	v_mfma_f32_32x32x16_bf16 v[16:31], v[156:159], v[176:179], v[16:31]
	v_max3_f32 v151, v151, v78, v79
	v_mov_b32_e32 v152, v151
	s_nop 1
	v_permlane32_swap_b32_e32 v151, v152
	v_max_f32_e32 v152, v152, v152
	v_max_f32_e32 v151, v151, v151
	v_max_f32_e32 v151, v151, v152
	v_sub_f32_e32 v152, v151, v148
	v_cmp_ge_f32_e32 vcc, s64, v152
	v_max_f32_e32 v152, v148, v148
	v_max_f32_e32 v151, v152, v151
	v_mfma_f32_32x32x16_bf16 v[16:31], v[160:163], v[180:183], v[16:31]
	v_sub_f32_e32 v152, v148, v151
	v_mul_f32_e32 v152, 0x3e38aa3b, v152
	v_exp_f32_e32 v152, v152
	s_cmp_eq_u64 vcc, exec
	s_cselect_b64 s[8:9], -1, 0
	v_cndmask_b32_e64 v152, v152, 1.0, s[8:9]
	v_cmp_gt_f32_e32 vcc, 1.0, v152
	s_cbranch_vccz .LBB0_473
	s_and_saveexec_b64 s[10:11], s[6:7]
	ds_write_b32 v136, v152 offset:49280
	s_or_b64 exec, exec, s[10:11]
	s_waitcnt lgkmcnt(0)
	v_add_u32_e32 v153, v125, v192
	ds_read_b128 v[112:115], v153 offset:49376
	ds_read_b128 v[116:119], v153 offset:49344
	ds_read_b128 v[120:123], v153 offset:49312
	ds_read_b128 v[154:157], v153 offset:49280
	s_waitcnt lgkmcnt(3)
	v_pk_mul_f32 v[12:13], v[12:13], v[112:113]
	s_waitcnt lgkmcnt(2)
	v_pk_mul_f32 v[8:9], v[8:9], v[116:117]
	s_waitcnt lgkmcnt(1)
	v_pk_mul_f32 v[4:5], v[4:5], v[120:121]
	v_pk_mul_f32 v[14:15], v[14:15], v[114:115]
	v_pk_mul_f32 v[10:11], v[10:11], v[118:119]
	v_pk_mul_f32 v[6:7], v[6:7], v[122:123]
	s_waitcnt lgkmcnt(0)
	v_pk_mul_f32 v[2:3], v[2:3], v[156:157]
	v_pk_mul_f32 v[0:1], v[0:1], v[154:155]
	v_pk_mul_f32 v[60:61], v[60:61], v[112:113]
	v_pk_mul_f32 v[56:57], v[56:57], v[116:117]
	v_pk_mul_f32 v[52:53], v[52:53], v[120:121]
	v_pk_mul_f32 v[62:63], v[62:63], v[114:115]
	v_pk_mul_f32 v[58:59], v[58:59], v[118:119]
	v_pk_mul_f32 v[54:55], v[54:55], v[122:123]
	v_pk_mul_f32 v[50:51], v[50:51], v[156:157]
	v_pk_mul_f32 v[48:49], v[48:49], v[154:155]
	v_pk_mul_f32 v[44:45], v[44:45], v[112:113]
	v_pk_mul_f32 v[40:41], v[40:41], v[116:117]
	v_pk_mul_f32 v[36:37], v[36:37], v[120:121]
	v_pk_mul_f32 v[46:47], v[46:47], v[114:115]
	v_pk_mul_f32 v[42:43], v[42:43], v[118:119]
	v_pk_mul_f32 v[38:39], v[38:39], v[122:123]
	v_pk_mul_f32 v[34:35], v[34:35], v[156:157]
	v_pk_mul_f32 v[32:33], v[32:33], v[154:155]
	v_pk_mul_f32 v[28:29], v[28:29], v[112:113]
	v_pk_mul_f32 v[24:25], v[24:25], v[116:117]
	v_pk_mul_f32 v[20:21], v[20:21], v[120:121]
	v_pk_mul_f32 v[30:31], v[30:31], v[114:115]
	v_pk_mul_f32 v[26:27], v[26:27], v[118:119]
	v_pk_mul_f32 v[22:23], v[22:23], v[122:123]
	v_pk_mul_f32 v[18:19], v[18:19], v[156:157]
	v_pk_mul_f32 v[16:17], v[16:17], v[154:155]
; #define SBAR() __builtin_amdgcn_sched_barrier(0)
; #define SLOAD(k0) do { vs0 = *(const bf16x8*)(vp0 + (long)(k0) * ldv); vs1 = *(const bf16x8*)(vp0 + (long)((k0) + 32) * ldv); \
;     ksg[0] = *(const bf16x8*)(kp0 + (long)(k0) * ldk0); \
;     if constexpr (DQK == 192) { ksg[1] = *(const bf16x8*)(kp0 + (long)((k0) + 32) * ldk0); ksg[2] = *(const bf16x8*)(kp2 + (long)(k0) * ldk1); } } while (0)
; #define RESC(a) do { if (__any((a) < 1.f)) { if (hi == 0) al_l[r32] = (a); asm volatile("s_waitcnt lgkmcnt(0)" ::: "memory"); \
;     _Pragma("unroll") for (int d = 0; d < 4; ++d) _Pragma("unroll") for (int r = 0; r < 16; ++r) o[d][r] *= al_l[crow(r, hi)]; } } while (0)
; DEVI void partialSM(f32x16& p0, f32x16& p1, float& m_reg, float& mn, float& alpha, float scale) {
;     ...
;   else { mn = fmaxf(m_reg, pmax); alpha = __builtin_amdgcn_exp2f((m_reg - mn) * C); m_reg = mn; }
;   const float mnC = -mn * C;
; #pragma unroll
;   for (int r = 0; r < 16; ++r) p0[r] = fmaf(p0[r], C, mnC);
; #pragma unroll
;   for (int r = 0; r < 16; ++r) p1[r] = fmaf(p1[r], C, mnC);
; #pragma unroll
;   for (int r = 0; r < 16; ++r) p0[r] = __builtin_amdgcn_exp2f(p0[r]);
; }
; DEVI void finishSM(f32x16& p0, f32x16& p1, float alpha, float& l_reg, bf16x8& pa0, bf16x8& pa1, bf16x8& pa2, bf16x8& pa3) {
; #pragma unroll
;   for (int r = 0; r < 16; ++r) p1[r] = __builtin_amdgcn_exp2f(p1[r]);
;   float ps = 0;
; #pragma unroll
;   for (int r = 0; r < 16; ++r) ps += p0[r];
; #pragma unroll
;   for (int r = 0; r < 16; ++r) ps += p1[r];
;   { auto rr = __builtin_amdgcn_permlane32_swap(__float_as_uint(ps), __float_as_uint(ps), false, false);
;     ps = __uint_as_float(rr[0]) + __uint_as_float(rr[1]); }
;   l_reg = l_reg * alpha + ps;
;   PK4(p0, 0, pa0); PK4(p0, 8, pa1); PK4(p1, 0, pa2); PK4(p1, 8, pa3);
; template <int DQK, bool PIPE>
; DEVI void attn_body(const u16* __restrict__ Qb, int ldq, const u16* __restrict__ K0, int ldk0, const u16* __restrict__ K1, int ldk1,
;                     const u16* __restrict__ Vh, int ldv, u16* __restrict__ Ob, int ldo, int seq, float scale, char* lds) {
;     ...
;       RESC(alB); __syncthreads();
;       SBAR(); QKT(pA0, pA1, K_lds);
;       finishSM(pB0, pB1, alB, l_reg, pa0, pa1, pa2, pa3); SBAR();
;       SLOAD((j + 2) * 64); SBAR();
;       pv_d0(o, vb0 + SHM_V, pa0, pa1, pa2, pa3); partialSM(pA0, pA1, m_reg, mnA, alA, scale);
.LBB0_473:
	v_cndmask_b32_e64 v148, v151, v148, s[8:9]
	v_mul_f32_e32 v153, 0xbe38aa3b, v148
	v_fmamk_f32 v84, v84, 0x3e38aa3b, v153
	v_exp_f32_e32 v151, v84
	v_fmamk_f32 v80, v80, 0x3e38aa3b, v153
	v_fmamk_f32 v81, v81, 0x3e38aa3b, v153
	v_fmamk_f32 v82, v82, 0x3e38aa3b, v153
	v_fmamk_f32 v83, v83, 0x3e38aa3b, v153
	v_fmamk_f32 v85, v85, 0x3e38aa3b, v153
	v_fmamk_f32 v86, v86, 0x3e38aa3b, v153
	v_fmamk_f32 v87, v87, 0x3e38aa3b, v153
	v_fmamk_f32 v88, v88, 0x3e38aa3b, v153
	v_fmamk_f32 v89, v89, 0x3e38aa3b, v153
	v_fmamk_f32 v90, v90, 0x3e38aa3b, v153
	v_fmamk_f32 v91, v91, 0x3e38aa3b, v153
	v_fmamk_f32 v92, v92, 0x3e38aa3b, v153
	v_fmamk_f32 v93, v93, 0x3e38aa3b, v153
	v_fmamk_f32 v94, v94, 0x3e38aa3b, v153
	v_fmamk_f32 v95, v95, 0x3e38aa3b, v153
	v_fmamk_f32 v165, v64, 0x3e38aa3b, v153
	v_fmamk_f32 v166, v65, 0x3e38aa3b, v153
	v_fmamk_f32 v167, v66, 0x3e38aa3b, v153
	v_fmamk_f32 v168, v67, 0x3e38aa3b, v153
	v_fmamk_f32 v169, v68, 0x3e38aa3b, v153
	v_fmamk_f32 v158, v69, 0x3e38aa3b, v153
	v_fmamk_f32 v159, v70, 0x3e38aa3b, v153
	v_fmamk_f32 v160, v71, 0x3e38aa3b, v153
	v_fmamk_f32 v161, v72, 0x3e38aa3b, v153
	v_fmamk_f32 v162, v73, 0x3e38aa3b, v153
	v_fmamk_f32 v163, v74, 0x3e38aa3b, v153
	v_fmamk_f32 v164, v75, 0x3e38aa3b, v153
	v_fmamk_f32 v154, v76, 0x3e38aa3b, v153
	v_fmamk_f32 v170, v77, 0x3e38aa3b, v153
	v_fmamk_f32 v171, v78, 0x3e38aa3b, v153
	v_fmac_f32_e32 v153, 0x3e38aa3b, v79
	v_exp_f32_e32 v120, v80
	v_exp_f32_e32 v121, v81
	v_exp_f32_e32 v122, v82
	v_exp_f32_e32 v123, v83
	v_exp_f32_e32 v155, v85
	v_exp_f32_e32 v156, v86
	v_exp_f32_e32 v157, v87
	v_exp_f32_e32 v112, v88
	v_exp_f32_e32 v113, v89
	v_exp_f32_e32 v114, v90
	v_exp_f32_e32 v115, v91
	v_exp_f32_e32 v116, v92
	v_exp_f32_e32 v117, v93
	v_exp_f32_e32 v118, v94
	v_exp_f32_e32 v119, v95
	s_waitcnt lgkmcnt(0)
	s_barrier
	ds_read_b128 v[64:67], v143 offset:32768
	ds_read_b128 v[68:71], v143 offset:36864
	ds_read_b128 v[172:175], v144 offset:32768
	ds_read_b128 v[176:179], v144 offset:36864
	v_exp_f32_e32 v183, v153
	v_add_f32_e32 v153, 0, v120
	s_waitcnt lgkmcnt(3)
	v_mfma_f32_32x32x16_bf16 v[80:95], v[64:67], v[100:103], 0
	v_add_f32_e32 v153, v121, v153
	v_add_f32_e32 v153, v122, v153
	v_add_f32_e32 v153, v123, v153
	v_add_f32_e32 v153, v151, v153
	v_add_f32_e32 v153, v155, v153
	v_add_f32_e32 v153, v156, v153
	v_add_f32_e32 v153, v157, v153
	s_waitcnt lgkmcnt(2)
	v_mfma_f32_32x32x16_bf16 v[64:79], v[68:71], v[100:103], 0
	v_add_f32_e32 v153, v112, v153
	v_add_f32_e32 v153, v113, v153
	v_add_f32_e32 v153, v114, v153
	v_add_f32_e32 v153, v115, v153
	v_add_f32_e32 v153, v116, v153
	v_exp_f32_e32 v166, v166
	v_add_f32_e32 v153, v117, v153
	s_waitcnt lgkmcnt(1)
	v_mfma_f32_32x32x16_bf16 v[80:95], v[172:175], v[96:99], v[80:95]
	v_exp_f32_e32 v167, v167
	v_add_f32_e32 v153, v118, v153
	v_exp_f32_e32 v168, v168
	v_add_f32_e32 v153, v119, v153
	v_exp_f32_e32 v169, v169
	v_exp_f32_e32 v180, v154
	v_exp_f32_e32 v181, v170
	s_waitcnt lgkmcnt(0)
	v_mfma_f32_32x32x16_bf16 v[64:79], v[176:179], v[96:99], v[64:79]
	ds_read_b128 v[172:175], v146 offset:32768
	ds_read_b128 v[176:179], v146 offset:36864
	v_exp_f32_e32 v182, v171
	s_waitcnt lgkmcnt(1)
	v_mfma_f32_32x32x16_bf16 v[80:95], v[172:175], v[108:111], v[80:95]
	s_waitcnt lgkmcnt(0)
	v_mfma_f32_32x32x16_bf16 v[64:79], v[176:179], v[108:111], v[64:79]
	ds_read_b128 v[172:175], v145 offset:32768
	ds_read_b128 v[176:179], v145 offset:36864
	s_waitcnt lgkmcnt(1)
	v_mfma_f32_32x32x16_bf16 v[80:95], v[172:175], v[104:107], v[80:95]
	v_exp_f32_e32 v172, v165
	v_exp_f32_e32 v173, v158
	v_exp_f32_e32 v174, v159
	v_exp_f32_e32 v175, v160
	v_add_f32_e32 v153, v172, v153
	v_add_f32_e32 v153, v166, v153
	v_add_f32_e32 v153, v167, v153
	v_add_f32_e32 v153, v168, v153
	s_waitcnt lgkmcnt(0)
	v_mfma_f32_32x32x16_bf16 v[64:79], v[176:179], v[104:107], v[64:79]
	v_exp_f32_e32 v176, v161
	v_add_f32_e32 v153, v169, v153
	v_exp_f32_e32 v177, v162
	v_add_f32_e32 v153, v173, v153
	v_exp_f32_e32 v178, v163
	v_add_f32_e32 v153, v174, v153
	v_exp_f32_e32 v179, v164
	v_add_f32_e32 v153, v175, v153
	v_add_f32_e32 v153, v176, v153
	v_add_f32_e32 v153, v177, v153
	v_add_f32_e32 v153, v178, v153
	v_add_f32_e32 v153, v179, v153
	v_add_f32_e32 v153, v180, v153
	v_add_f32_e32 v153, v181, v153
	v_add_f32_e32 v153, v182, v153
	v_add_f32_e32 v153, v183, v153
	v_mov_b32_e32 v154, v153
	s_nop 1
	v_permlane32_swap_b32_e32 v153, v154
	v_cvt_pk_bf16_f32 v158, v120, v121
	v_cvt_pk_bf16_f32 v159, v122, v123
	v_cvt_pk_bf16_f32 v160, v151, v155
	v_cvt_pk_bf16_f32 v161, v156, v157
	v_cvt_pk_bf16_f32 v162, v112, v113
	v_cvt_pk_bf16_f32 v163, v114, v115
	v_cvt_pk_bf16_f32 v164, v116, v117
	v_cvt_pk_bf16_f32 v165, v118, v119
	v_cvt_pk_bf16_f32 v166, v172, v166
	v_cvt_pk_bf16_f32 v167, v167, v168
	v_cvt_pk_bf16_f32 v168, v169, v173
	v_cvt_pk_bf16_f32 v169, v174, v175
	v_cvt_pk_bf16_f32 v170, v176, v177
	v_cvt_pk_bf16_f32 v171, v178, v179
	v_cvt_pk_bf16_f32 v172, v180, v181
	v_cvt_pk_bf16_f32 v173, v182, v183
	v_permlane32_swap_b32_e32 v158, v160
	v_permlane32_swap_b32_e32 v159, v161
	v_permlane32_swap_b32_e32 v162, v164
	v_permlane32_swap_b32_e32 v163, v165
	v_permlane32_swap_b32_e32 v166, v168
	v_permlane32_swap_b32_e32 v167, v169
	v_permlane32_swap_b32_e32 v170, v172
	v_permlane32_swap_b32_e32 v171, v173
	s_mov_b32 s8, 0x827f000
	v_add_co_u32_e32 v112, vcc, s8, v130
	s_mov_b32 s8, 0x8317000
	s_nop 0
	v_addc_co_u32_e32 v113, vcc, 0, v131, vcc
	v_add_co_u32_e32 v116, vcc, s8, v130
	s_mov_b32 s8, 0x827e000
	s_nop 0
	v_addc_co_u32_e32 v117, vcc, 0, v131, vcc
	v_add_co_u32_e32 v120, vcc, s8, v132
	global_load_dwordx4 v[112:115], v[112:113], off
	s_nop 0
	global_load_dwordx4 v[116:119], v[116:117], off
	v_addc_co_u32_e32 v121, vcc, 0, v133, vcc
	global_load_dwordx4 v[120:123], v[120:121], off offset:2048
	ds_read_b64_tr_b16 v[130:131], v138 offset:0
	ds_read_b64_tr_b16 v[132:133], v138 offset:0x800
	ds_read_b64_tr_b16 v[174:175], v138 offset:0x1000
	ds_read_b64_tr_b16 v[176:177], v138 offset:0x1800
	ds_read_b64_tr_b16 v[178:179], v138 offset:0x2000
	ds_read_b64_tr_b16 v[180:181], v138 offset:0x2800
	ds_read_b64_tr_b16 v[182:183], v138 offset:0x3000
	ds_read_b64_tr_b16 v[184:185], v138 offset:0x3800
	s_waitcnt lgkmcnt(0)
; template <int D0> DEVI void pv_one(f32x16& od, int vb, bf16x8 pa0, bf16x8 pa1, bf16x8 pa2, bf16x8 pa3) {
;     ...
;   od = __builtin_amdgcn_mfma_f32_32x32x16_bf16(pa0, PK(l0, h0), od, 0, 0, 0);
;   od = __builtin_amdgcn_mfma_f32_32x32x16_bf16(pa1, PK(l1, h1), od, 0, 0, 0);
;   od = __builtin_amdgcn_mfma_f32_32x32x16_bf16(pa2, PK(l2, h2), od, 0, 0, 0);
;   od = __builtin_amdgcn_mfma_f32_32x32x16_bf16(pa3, PK(l3, h3), od, 0, 0, 0);
;     ...
; }
; DEVI void pv_d0(f32x16* o, int vb, bf16x8 pa0, bf16x8 pa1, bf16x8 pa2, bf16x8 pa3) {
;   pv_one<0>(o[0], vb, pa0, pa1, pa2, pa3); pv_one<1>(o[1], vb, pa0, pa1, pa2, pa3); pv_one<2>(o[2], vb, pa0, pa1, pa2, pa3); pv_one<3>(o[3], vb, pa0, pa1, pa2, pa3);
; }
; DEVI void partialSM(f32x16& p0, f32x16& p1, float& m_reg, float& mn, float& alpha, float scale) {
;   const float C = scale * 1.4426950408889634f;
;   float pmax = p0[0];
; #pragma unroll
;   for (int r = 1; r < 16; ++r) pmax = fmaxf(pmax, p0[r]);
; #pragma unroll
;   for (int r = 0; r < 16; ++r) pmax = fmaxf(pmax, p1[r]);
;   { auto rr = __builtin_amdgcn_permlane32_swap(__float_as_uint(pmax), __float_as_uint(pmax), false, false);
;     pmax = fmaxf(__uint_as_float(rr[0]), __uint_as_float(rr[1])); }
;   if (__builtin_expect(__all(pmax - m_reg <= ATT_THR / scale), 1)) { mn = m_reg; alpha = 1.f; }
;   else { mn = fmaxf(m_reg, pmax); alpha = __builtin_amdgcn_exp2f((m_reg - mn) * C); m_reg = mn; }
; template <int DQK, bool PIPE>
; DEVI void attn_body(const u16* __restrict__ Qb, int ldq, const u16* __restrict__ K0, int ldk0, const u16* __restrict__ K1, int ldk1,
;                     const u16* __restrict__ Vh, int ldv, u16* __restrict__ Ob, int ldo, int seq, float scale, char* lds) {
;     ...
;   bf16x8 pa0, pa1, pa2, pa3; const int NT = seq / 64;
;   if constexpr (PIPE) {
;     f32x16 pA0, pA1, pB0, pB1; float mnA, mnB, alA, alB;
;     SLOAD(0); SWAIT(); SWRITE(0); __syncthreads();
;     QKT(pA0, pA1, K_lds); partialSM(pA0, pA1, m_reg, mnA, alA, scale);
;     SLOAD(64);
;     SWAIT(); SWRITE(1); __syncthreads();
;     for (int j = 1; j + 1 < NT; j += 2) {
;       SBAR(); QKT(pB0, pB1, K_lds + SHM_K);
;       finishSM(pA0, pA1, alA, l_reg, pa0, pa1, pa2, pa3); SBAR();
;       SLOAD((j + 1) * 64); SBAR();
;       pv_d0(o, vb0, pa0, pa1, pa2, pa3); partialSM(pB0, pB1, m_reg, mnB, alB, scale);
;       __syncthreads(); SWAIT(); SWRITE(0);
;       RESC(alB); __syncthreads();
	s_nop 0
	v_mfma_f32_32x32x16_bf16 v[0:15], v[158:161], v[130:133], v[0:15]
	ds_read_b64_tr_b16 v[130:131], v138 offset:0x200
	ds_read_b64_tr_b16 v[132:133], v138 offset:0xa00
	v_mfma_f32_32x32x16_bf16 v[0:15], v[162:165], v[174:177], v[0:15]
	ds_read_b64_tr_b16 v[174:175], v138 offset:0x1200
	ds_read_b64_tr_b16 v[176:177], v138 offset:0x1a00
	v_mfma_f32_32x32x16_bf16 v[0:15], v[166:169], v[178:181], v[0:15]
	ds_read_b64_tr_b16 v[178:179], v138 offset:0x2200
	ds_read_b64_tr_b16 v[180:181], v138 offset:0x2a00
	v_mfma_f32_32x32x16_bf16 v[0:15], v[170:173], v[182:185], v[0:15]
	ds_read_b64_tr_b16 v[182:183], v138 offset:0x3200
	ds_read_b64_tr_b16 v[184:185], v138 offset:0x3a00
	s_waitcnt lgkmcnt(0)
	v_mfma_f32_32x32x16_bf16 v[48:63], v[158:161], v[130:133], v[48:63]
	ds_read_b64_tr_b16 v[130:131], v138 offset:0x400
	ds_read_b64_tr_b16 v[132:133], v138 offset:0xc00
	v_mfma_f32_32x32x16_bf16 v[48:63], v[162:165], v[174:177], v[48:63]
	ds_read_b64_tr_b16 v[174:175], v138 offset:0x1400
	ds_read_b64_tr_b16 v[176:177], v138 offset:0x1c00
	v_mfma_f32_32x32x16_bf16 v[48:63], v[166:169], v[178:181], v[48:63]
	ds_read_b64_tr_b16 v[178:179], v138 offset:0x2400
	ds_read_b64_tr_b16 v[180:181], v138 offset:0x2c00
	v_mfma_f32_32x32x16_bf16 v[48:63], v[170:173], v[182:185], v[48:63]
	ds_read_b64_tr_b16 v[182:183], v138 offset:0x3400
	ds_read_b64_tr_b16 v[184:185], v138 offset:0x3c00
	s_waitcnt lgkmcnt(0)
	v_mfma_f32_32x32x16_bf16 v[32:47], v[158:161], v[130:133], v[32:47]
	ds_read_b64_tr_b16 v[130:131], v138 offset:0x600
	ds_read_b64_tr_b16 v[132:133], v138 offset:0xe00
	v_mfma_f32_32x32x16_bf16 v[32:47], v[162:165], v[174:177], v[32:47]
	ds_read_b64_tr_b16 v[174:175], v138 offset:0x1600
	ds_read_b64_tr_b16 v[176:177], v138 offset:0x1e00
	v_mfma_f32_32x32x16_bf16 v[32:47], v[166:169], v[178:181], v[32:47]
	ds_read_b64_tr_b16 v[178:179], v138 offset:0x2600
	ds_read_b64_tr_b16 v[180:181], v138 offset:0x2e00
	v_mfma_f32_32x32x16_bf16 v[32:47], v[170:173], v[182:185], v[32:47]
	ds_read_b64_tr_b16 v[182:183], v138 offset:0x3600
	ds_read_b64_tr_b16 v[184:185], v138 offset:0x3e00
	s_waitcnt lgkmcnt(0)
	v_mfma_f32_32x32x16_bf16 v[16:31], v[158:161], v[130:133], v[16:31]
	v_max_f32_e32 v130, v81, v81
	v_max_f32_e32 v131, v80, v80
	v_max_f32_e32 v130, v131, v130
	v_max3_f32 v130, v130, v82, v83
	v_max3_f32 v130, v130, v84, v85
	v_max3_f32 v130, v130, v86, v87
	v_max3_f32 v130, v130, v88, v89
	v_max3_f32 v130, v130, v90, v91
	v_max3_f32 v130, v130, v92, v93
	v_mfma_f32_32x32x16_bf16 v[16:31], v[162:165], v[174:177], v[16:31]
	v_max3_f32 v130, v130, v94, v95
	v_max3_f32 v130, v130, v64, v65
	v_max3_f32 v130, v130, v66, v67
	v_max3_f32 v130, v130, v68, v69
	v_max3_f32 v130, v130, v70, v71
	v_max3_f32 v130, v130, v72, v73
	v_max3_f32 v130, v130, v74, v75
	v_max3_f32 v130, v130, v76, v77
	v_mfma_f32_32x32x16_bf16 v[16:31], v[166:169], v[178:181], v[16:31]
	v_max3_f32 v130, v130, v78, v79
	v_mov_b32_e32 v131, v130
	s_nop 1
	v_permlane32_swap_b32_e32 v130, v131
	v_max_f32_e32 v131, v131, v131
	v_max_f32_e32 v130, v130, v130
	v_max_f32_e32 v130, v130, v131
	v_sub_f32_e32 v131, v130, v148
	v_cmp_ge_f32_e32 vcc, s64, v131
	v_max_f32_e32 v131, v148, v148
	v_max_f32_e32 v130, v131, v130
	v_mfma_f32_32x32x16_bf16 v[16:31], v[170:173], v[182:185], v[16:31]
	v_sub_f32_e32 v131, v148, v130
	v_mul_f32_e32 v131, 0x3e38aa3b, v131
	v_exp_f32_e32 v131, v131
	s_cmp_eq_u64 vcc, exec
	s_cselect_b64 s[8:9], -1, 0
	s_waitcnt vmcnt(0)
	v_cndmask_b32_e64 v151, v131, 1.0, s[8:9]
	v_cmp_gt_f32_e32 vcc, 1.0, v151
	s_waitcnt vmcnt(2)
	ds_write_b128 v141, v[112:115] offset:16384
	s_waitcnt vmcnt(1)
	ds_write_b128 v142, v[116:119] offset:16384
	s_waitcnt vmcnt(0)
	ds_write_b128 v140, v[120:123] offset:40960
	s_cbranch_vccz .LBB0_477
	s_and_saveexec_b64 s[10:11], s[6:7]
	ds_write_b32 v136, v151 offset:49280
	s_or_b64 exec, exec, s[10:11]
	s_waitcnt lgkmcnt(0)
	v_add_u32_e32 v131, v125, v192
	ds_read_b128 v[112:115], v131 offset:49376
	ds_read_b128 v[116:119], v131 offset:49344
	ds_read_b128 v[120:123], v131 offset:49312
	ds_read_b128 v[156:159], v131 offset:49280
	s_waitcnt lgkmcnt(3)
	v_pk_mul_f32 v[12:13], v[12:13], v[112:113]
	s_waitcnt lgkmcnt(2)
	v_pk_mul_f32 v[8:9], v[8:9], v[116:117]
	s_waitcnt lgkmcnt(1)
	v_pk_mul_f32 v[4:5], v[4:5], v[120:121]
	v_pk_mul_f32 v[14:15], v[14:15], v[114:115]
	v_pk_mul_f32 v[10:11], v[10:11], v[118:119]
	v_pk_mul_f32 v[6:7], v[6:7], v[122:123]
	s_waitcnt lgkmcnt(0)
	v_pk_mul_f32 v[2:3], v[2:3], v[158:159]
	v_pk_mul_f32 v[0:1], v[0:1], v[156:157]
	v_pk_mul_f32 v[60:61], v[60:61], v[112:113]
	v_pk_mul_f32 v[56:57], v[56:57], v[116:117]
	v_pk_mul_f32 v[52:53], v[52:53], v[120:121]
	v_pk_mul_f32 v[62:63], v[62:63], v[114:115]
	v_pk_mul_f32 v[58:59], v[58:59], v[118:119]
	v_pk_mul_f32 v[54:55], v[54:55], v[122:123]
	v_pk_mul_f32 v[50:51], v[50:51], v[158:159]
	v_pk_mul_f32 v[48:49], v[48:49], v[156:157]
	v_pk_mul_f32 v[44:45], v[44:45], v[112:113]
	v_pk_mul_f32 v[40:41], v[40:41], v[116:117]
	v_pk_mul_f32 v[36:37], v[36:37], v[120:121]
	v_pk_mul_f32 v[46:47], v[46:47], v[114:115]
	v_pk_mul_f32 v[42:43], v[42:43], v[118:119]
	v_pk_mul_f32 v[38:39], v[38:39], v[122:123]
	v_pk_mul_f32 v[34:35], v[34:35], v[158:159]
	v_pk_mul_f32 v[32:33], v[32:33], v[156:157]
	v_pk_mul_f32 v[28:29], v[28:29], v[112:113]
	v_pk_mul_f32 v[24:25], v[24:25], v[116:117]
	v_pk_mul_f32 v[20:21], v[20:21], v[120:121]
	v_pk_mul_f32 v[30:31], v[30:31], v[114:115]
	v_pk_mul_f32 v[26:27], v[26:27], v[118:119]
	v_pk_mul_f32 v[22:23], v[22:23], v[122:123]
	v_pk_mul_f32 v[18:19], v[18:19], v[158:159]
	v_pk_mul_f32 v[16:17], v[16:17], v[156:157]
; #define SBAR() __builtin_amdgcn_sched_barrier(0)
; #define SLOAD(k0) do { vs0 = *(const bf16x8*)(vp0 + (long)(k0) * ldv); vs1 = *(const bf16x8*)(vp0 + (long)((k0) + 32) * ldv); \
;     ksg[0] = *(const bf16x8*)(kp0 + (long)(k0) * ldk0); \
;     if constexpr (DQK == 192) { ksg[1] = *(const bf16x8*)(kp0 + (long)((k0) + 32) * ldk0); ksg[2] = *(const bf16x8*)(kp2 + (long)(k0) * ldk1); } } while (0)
; #define SWAIT() asm volatile("s_waitcnt vmcnt(0)" ::: "memory")
; DEVI void partialSM(f32x16& p0, f32x16& p1, float& m_reg, float& mn, float& alpha, float scale) {
;   const float C = scale * 1.4426950408889634f;
;   float pmax = p0[0];
; #pragma unroll
;   for (int r = 1; r < 16; ++r) pmax = fmaxf(pmax, p0[r]);
; #pragma unroll
;   for (int r = 0; r < 16; ++r) pmax = fmaxf(pmax, p1[r]);
;   { auto rr = __builtin_amdgcn_permlane32_swap(__float_as_uint(pmax), __float_as_uint(pmax), false, false);
;     pmax = fmaxf(__uint_as_float(rr[0]), __uint_as_float(rr[1])); }
;   if (__builtin_expect(__all(pmax - m_reg <= ATT_THR / scale), 1)) { mn = m_reg; alpha = 1.f; }
;   else { mn = fmaxf(m_reg, pmax); alpha = __builtin_amdgcn_exp2f((m_reg - mn) * C); m_reg = mn; }
;   const float mnC = -mn * C;
; #pragma unroll
;   for (int r = 0; r < 16; ++r) p0[r] = fmaf(p0[r], C, mnC);
; #pragma unroll
;   for (int r = 0; r < 16; ++r) p1[r] = fmaf(p1[r], C, mnC);
; #pragma unroll
;   for (int r = 0; r < 16; ++r) p0[r] = __builtin_amdgcn_exp2f(p0[r]);
; }
; template <int DQK, bool PIPE>
; DEVI void attn_body(const u16* __restrict__ Qb, int ldq, const u16* __restrict__ K0, int ldk0, const u16* __restrict__ K1, int ldk1,
;                     const u16* __restrict__ Vh, int ldv, u16* __restrict__ Ob, int ldo, int seq, float scale, char* lds) {
;     ...
;       __syncthreads(); SWAIT(); SWRITE(0);
;       RESC(alB); __syncthreads();
;       SBAR(); QKT(pA0, pA1, K_lds);
;       finishSM(pB0, pB1, alB, l_reg, pa0, pa1, pa2, pa3); SBAR();
;       SLOAD((j + 2) * 64); SBAR();
;       pv_d0(o, vb0 + SHM_V, pa0, pa1, pa2, pa3); partialSM(pA0, pA1, m_reg, mnA, alA, scale);
;       __syncthreads(); SWAIT(); SWRITE(1);
;       RESC(alA); __syncthreads();
;     }
.LBB0_477:
	v_cndmask_b32_e64 v148, v130, v148, s[8:9]
	v_mul_f32_e32 v112, 0xbe38aa3b, v148
	v_mov_b32_e32 v113, v112
	v_fmamk_f32 v80, v80, 0x3e38aa3b, v112
	v_fmamk_f32 v81, v81, 0x3e38aa3b, v112
	v_fmamk_f32 v82, v82, 0x3e38aa3b, v112
	v_fmamk_f32 v83, v83, 0x3e38aa3b, v112
	v_fmamk_f32 v84, v84, 0x3e38aa3b, v112
	v_fmamk_f32 v85, v85, 0x3e38aa3b, v112
	v_fmamk_f32 v86, v86, 0x3e38aa3b, v112
	v_fmamk_f32 v87, v87, 0x3e38aa3b, v112
	v_fmamk_f32 v88, v88, 0x3e38aa3b, v112
	v_fmamk_f32 v89, v89, 0x3e38aa3b, v112
	v_fmamk_f32 v90, v90, 0x3e38aa3b, v112
	v_fmamk_f32 v91, v91, 0x3e38aa3b, v112
	v_fmamk_f32 v92, v92, 0x3e38aa3b, v112
	v_fmamk_f32 v93, v93, 0x3e38aa3b, v112
	v_fmamk_f32 v94, v94, 0x3e38aa3b, v112
	v_fmac_f32_e32 v113, 0x3e38aa3b, v95
	v_exp_f32_e32 v157, v80
	v_exp_f32_e32 v159, v81
	v_exp_f32_e32 v161, v82
	v_exp_f32_e32 v163, v83
	v_exp_f32_e32 v165, v84
	v_exp_f32_e32 v167, v85
	v_exp_f32_e32 v168, v86
	v_exp_f32_e32 v170, v87
	v_exp_f32_e32 v155, v88
	v_exp_f32_e32 v156, v89
	v_exp_f32_e32 v158, v90
	v_exp_f32_e32 v160, v91
	v_exp_f32_e32 v162, v92
	v_exp_f32_e32 v164, v93
	v_exp_f32_e32 v166, v94
	v_exp_f32_e32 v169, v113
	v_pk_fma_f32 v[132:133], v[64:65], s[20:21], v[112:113] op_sel_hi:[1,0,0]
	v_add_f32_e32 v64, v149, v150
	v_fmac_f32_e32 v64, v147, v137
	v_add_f32_e32 v137, v153, v154
	s_add_i32 s15, s15, 2
	v_pk_fma_f32 v[130:131], v[66:67], s[20:21], v[112:113] op_sel_hi:[1,0,0]
	v_pk_fma_f32 v[120:121], v[68:69], s[20:21], v[112:113] op_sel_hi:[1,0,0]
	v_pk_fma_f32 v[116:117], v[70:71], s[20:21], v[112:113] op_sel_hi:[1,0,0]
	v_pk_fma_f32 v[114:115], v[72:73], s[20:21], v[112:113] op_sel_hi:[1,0,0]
	v_pk_fma_f32 v[122:123], v[74:75], s[20:21], v[112:113] op_sel_hi:[1,0,0]
	v_pk_fma_f32 v[118:119], v[76:77], s[20:21], v[112:113] op_sel_hi:[1,0,0]
	v_pk_fma_f32 v[112:113], v[78:79], s[20:21], v[112:113] op_sel_hi:[1,0,0]
	v_fmac_f32_e32 v137, v64, v152
	v_lshl_add_u64 v[126:127], v[126:127], 0, s[22:23]
	s_cmpk_gt_u32 s15, 0x80
	v_lshl_add_u64 v[128:129], v[128:129], 0, s[22:23]
	v_xor_b32_e32 v138, 0x10000, v138
	v_xor_b32_e32 v139, 0x10000, v139
	v_xor_b32_e32 v140, 0x10000, v140
	v_xor_b32_e32 v141, 0x10000, v141
	v_xor_b32_e32 v142, 0x10000, v142
	s_waitcnt lgkmcnt(0)
	s_barrier
	s_cbranch_scc1 .LBB0_479
	v_mov_b32_e32 v147, v151
	s_branch .LBB0_469
